# phase-0 rmsnorm rows: two-set pipelined loop, gain loaded once (hipcc final rmsnorm kept)
# speedup vs baseline: 1.0062x; 1.0024x over previous
; DI int bidx() { int b = blockIdx.x; asm volatile("" : "+s"(b)); return b; }
; DI void rmsnorm_rows(const float* x, const float* g, bf16_t* outb, float* outf) {
;     ...
;   for (int it = bidx(); it < NTOK / 16; it += gridDim.x) {
;     float4 v[2][4]; float ss[2] = {0.f, 0.f};
; #pragma unroll
;     for (int rr = 0; rr < 2; ++rr) {
;       const float* xr = x + (size_t)(it * 16 + rr * 8 + w) * 1024;
; #pragma unroll
;       for (int i = 0; i < 4; ++i) v[rr][i] = *(const float4*)(xr + lane * 4 + 256 * i);
;     }
;     float4 gg[4];
; #pragma unroll
;     for (int i = 0; i < 4; ++i) gg[i] = *(const float4*)(g + lane * 4 + 256 * i);
.LBB0_147:
	global_load_dwordx4 v[188:191], v[52:53], off
	global_load_dwordx4 v[184:187], v[52:53], off offset:1024
	global_load_dwordx4 v[180:183], v[52:53], off offset:2048
	global_load_dwordx4 v[176:179], v[52:53], off offset:3072
	s_mov_b32 s2, 0x3a800000
	s_mov_b64 s[98:99], 0x8000
	s_mov_b64 s[100:101], 0x4000
	v_mov_b32_e32 v195, 0
	v_lshlrev_b32_e32 v194, 12, v56
	v_lshl_add_u64 v[196:197], v[50:51], 0, v[194:195]
	global_load_dwordx4 v[14:17], v[196:197], off
	global_load_dwordx4 v[22:25], v[196:197], off offset:1024
	global_load_dwordx4 v[2:5], v[196:197], off offset:2048
	global_load_dwordx4 v[6:9], v[196:197], off offset:3072
	v_lshl_add_u64 v[198:199], v[196:197], 0, s[98:99]
	global_load_dwordx4 v[38:41], v[198:199], off
	global_load_dwordx4 v[30:33], v[198:199], off offset:1024
	global_load_dwordx4 v[26:29], v[198:199], off offset:2048
	global_load_dwordx4 v[10:13], v[198:199], off offset:3072
	v_lshlrev_b32_e32 v194, 11, v56
	v_lshl_add_u64 v[60:61], v[54:55], 0, v[194:195]
	v_lshl_add_u64 v[58:59], v[60:61], 0, s[100:101]
	v_add_u32_e32 v56, s1, v56
.Lrn_loop:
	s_add_i32 s20, s20, s0
	s_cmpk_lt_i32 s20, 0x400
	s_cbranch_scc0 .Lrn_lastA
	v_lshlrev_b32_e32 v194, 12, v56
	v_lshl_add_u64 v[196:197], v[50:51], 0, v[194:195]
	global_load_dwordx4 v[102:105], v[196:197], off
	global_load_dwordx4 v[110:113], v[196:197], off offset:1024
	global_load_dwordx4 v[90:93], v[196:197], off offset:2048
	global_load_dwordx4 v[94:97], v[196:197], off offset:3072
	v_lshl_add_u64 v[198:199], v[196:197], 0, s[98:99]
	global_load_dwordx4 v[126:129], v[198:199], off
	global_load_dwordx4 v[118:121], v[198:199], off offset:1024
	global_load_dwordx4 v[114:117], v[198:199], off offset:2048
	global_load_dwordx4 v[98:101], v[198:199], off offset:3072
	v_lshlrev_b32_e32 v194, 11, v56
	v_lshl_add_u64 v[148:149], v[54:55], 0, v[194:195]
	v_lshl_add_u64 v[146:147], v[148:149], 0, s[100:101]
	v_add_u32_e32 v56, s1, v56
	s_waitcnt vmcnt(8)
	s_branch .Lrn_compA

; DI unsigned pack2(float a, float b) { fv2 v = {a, b}; return __builtin_bit_cast(unsigned, __builtin_convertvector(v, bfv2)); }
; DI float wave_sum_fast(float v) { v = fdpp_add(v, 0); v = fdpp_add(v, 1); v = fdpp_add(v, 2); v = fdpp_add(v, 3); v = xor16_sum(v); return xor32_sum(v); }
; DI void rmsnorm_rows(const float* x, const float* g, bf16_t* outb, float* outf) {
;     ...
;     for (int rr = 0; rr < 2; ++rr) {
; #pragma unroll
;       for (int i = 0; i < 4; ++i) ss[rr] += v[rr][i].x * v[rr][i].x + v[rr][i].y * v[rr][i].y + v[rr][i].z * v[rr][i].z + v[rr][i].w * v[rr][i].w;
;       ss[rr] = wave_sum_fast(ss[rr]);
;     }
; #pragma unroll
;     for (int rr = 0; rr < 2; ++rr) {
;       const int row = it * 16 + rr * 8 + w;
;       const float rs = rsqrtf(ss[rr] * (1.f / 1024.f) + 1e-6f);
; #pragma unroll
;       for (int i = 0; i < 4; ++i) {
;         const float o0 = v[rr][i].x * rs * gg[i].x, o1 = v[rr][i].y * rs * gg[i].y, o2 = v[rr][i].z * rs * gg[i].z, o3 = v[rr][i].w * rs * gg[i].w;
;         if (outf) { *(float4*)(outf + (size_t)row * 1024 + lane * 4 + 256 * i) = make_float4(o0, o1, o2, o3); }
;         else { uint2 o; o.x = pack2(o0, o1); o.y = pack2(o2, o3); *(uint2*)(outb + (size_t)row * 1024 + lane * 4 + 256 * i) = o; }
;       }
;     }
.Lrn_compA:
	v_pk_mul_f32 v[64:65], v[14:15], v[14:15]
	v_pk_mul_f32 v[68:69], v[22:23], v[22:23]
	v_pk_mul_f32 v[62:63], v[16:17], v[16:17]
	v_pk_mul_f32 v[72:73], v[6:7], v[6:7]
	v_pk_mul_f32 v[66:67], v[24:25], v[24:25]
	v_pk_mul_f32 v[70:71], v[2:3], v[2:3]
	v_pk_mul_f32 v[76:77], v[8:9], v[8:9]
	v_add_f32_e32 v0, v68, v69
	v_add_f32_e32 v57, v64, v65
	v_add_f32_e32 v87, v72, v73
	v_pk_mul_f32 v[64:65], v[38:39], v[38:39]
	v_pk_mul_f32 v[68:69], v[30:31], v[30:31]
	v_add_f32_e32 v86, v70, v71
	v_pk_mul_f32 v[70:71], v[26:27], v[26:27]
	v_pk_mul_f32 v[78:79], v[40:41], v[40:41]
	v_pk_mul_f32 v[80:81], v[32:33], v[32:33]
	v_add_f32_e32 v68, v68, v69
	v_add_f32_e32 v64, v64, v65
	v_add_f32_e32 v0, v0, v66
	v_add_f32_e32 v57, v57, v62
	v_add_f32_e32 v66, v87, v76
	v_pk_mul_f32 v[74:75], v[4:5], v[4:5]
	v_pk_mul_f32 v[72:73], v[10:11], v[10:11]
	v_pk_mul_f32 v[82:83], v[28:29], v[28:29]
	v_add_f32_e32 v65, v70, v71
	v_add_f32_e32 v0, v0, v67
	v_add_f32_e32 v57, v57, v63
	v_add_f32_e32 v63, v66, v77
	v_add_f32_e32 v66, v68, v80
	v_add_f32_e32 v64, v64, v78
	v_pk_mul_f32 v[84:85], v[12:13], v[12:13]
	v_add_f32_e32 v69, v72, v73
	v_add_f32_e32 v62, v86, v74
	v_add_f32_e32 v65, v65, v82
	v_add_f32_e32 v66, v66, v81
	v_add_f32_e32 v0, v57, v0
	v_add_f32_e32 v57, v64, v79
	v_add_f32_e32 v62, v62, v75
	v_add_f32_e32 v67, v69, v84
	v_add_f32_e32 v64, v65, v83
	v_add_f32_e32 v57, v57, v66
	v_add_f32_e32 v65, v67, v85
	v_add_f32_e32 v0, v0, v62
	v_add_f32_e32 v57, v57, v64
	v_add_f32_e32 v0, v0, v63
	v_add_f32_e32 v57, v57, v65
	s_nop 0
	v_add_f32_dpp v0, v0, v0 quad_perm:[1,0,3,2] row_mask:0xf bank_mask:0xf bound_ctrl:1
	v_add_f32_dpp v57, v57, v57 quad_perm:[1,0,3,2] row_mask:0xf bank_mask:0xf bound_ctrl:1
	s_nop 0
	v_add_f32_dpp v0, v0, v0 quad_perm:[2,3,0,1] row_mask:0xf bank_mask:0xf bound_ctrl:1
	v_add_f32_dpp v57, v57, v57 quad_perm:[2,3,0,1] row_mask:0xf bank_mask:0xf bound_ctrl:1
	s_nop 0
	v_add_f32_dpp v0, v0, v0 row_half_mirror row_mask:0xf bank_mask:0xf bound_ctrl:1
	v_add_f32_dpp v57, v57, v57 row_half_mirror row_mask:0xf bank_mask:0xf bound_ctrl:1
	s_nop 0
	v_add_f32_dpp v0, v0, v0 row_mirror row_mask:0xf bank_mask:0xf bound_ctrl:1
	v_add_f32_dpp v57, v57, v57 row_mirror row_mask:0xf bank_mask:0xf bound_ctrl:1
	v_mov_b32_e32 v62, v0
	v_mov_b32_e32 v64, v57
	s_nop 0
	v_permlane16_swap_b32_e32 v0, v62
	v_permlane16_swap_b32_e32 v57, v64
	v_add_f32_e32 v63, v0, v62
	v_add_f32_e32 v62, v57, v64
	v_mov_b32_e32 v65, v63
	v_mov_b32_e32 v64, v62
	s_nop 0
	v_permlane32_swap_b32_e32 v63, v65
	v_permlane32_swap_b32_e32 v62, v64
	v_pk_add_f32 v[62:63], v[62:63], v[64:65]
	s_nop 0
	v_pk_fma_f32 v[62:63], v[62:63], s[2:3], v[200:201] op_sel_hi:[1,0,0]
	s_nop 0
	v_mul_f32_e32 v0, 0x4b800000, v63
	v_cmp_gt_f32_e32 vcc, s3, v63
	s_nop 1
	v_cndmask_b32_e32 v0, v63, v0, vcc
	v_rsq_f32_e32 v0, v0
	s_nop 0
	v_mul_f32_e32 v57, 0x45800000, v0
	v_cndmask_b32_e32 v0, v0, v57, vcc
	v_pk_mul_f32 v[2:3], v[2:3], v[0:1] op_sel_hi:[1,0]
	v_pk_mul_f32 v[4:5], v[4:5], v[0:1] op_sel_hi:[1,0]
	v_pk_mul_f32 v[2:3], v[180:181], v[2:3]
	v_pk_mul_f32 v[4:5], v[182:183], v[4:5]
	v_pk_mul_f32 v[14:15], v[14:15], v[0:1] op_sel_hi:[1,0]
	v_pk_mul_f32 v[16:17], v[16:17], v[0:1] op_sel_hi:[1,0]
	v_pk_mul_f32 v[22:23], v[22:23], v[0:1] op_sel_hi:[1,0]
	v_pk_mul_f32 v[24:25], v[24:25], v[0:1] op_sel_hi:[1,0]
	v_cvt_pk_bf16_f32 v2, v2, v3
	v_cvt_pk_bf16_f32 v3, v4, v5
	v_pk_mul_f32 v[4:5], v[6:7], v[0:1] op_sel_hi:[1,0]
	v_pk_mul_f32 v[6:7], v[8:9], v[0:1] op_sel_hi:[1,0]
	v_mul_f32_e32 v0, 0x4b800000, v62
	v_cmp_gt_f32_e32 vcc, s3, v62
	v_pk_mul_f32 v[14:15], v[188:189], v[14:15]
	v_pk_mul_f32 v[16:17], v[190:191], v[16:17]
	v_cndmask_b32_e32 v0, v62, v0, vcc
	v_rsq_f32_e32 v0, v0
	v_pk_mul_f32 v[22:23], v[184:185], v[22:23]
	v_pk_mul_f32 v[24:25], v[186:187], v[24:25]
	v_cvt_pk_bf16_f32 v14, v14, v15
	v_cvt_pk_bf16_f32 v15, v16, v17
	v_cvt_pk_bf16_f32 v16, v22, v23
	v_cvt_pk_bf16_f32 v17, v24, v25
	v_pk_mul_f32 v[4:5], v[176:177], v[4:5]
	v_pk_mul_f32 v[6:7], v[178:179], v[6:7]
	v_cvt_pk_bf16_f32 v4, v4, v5
	v_cvt_pk_bf16_f32 v5, v6, v7
	global_store_dwordx2 v[60:61], v[14:15], off
	global_store_dwordx2 v[60:61], v[16:17], off offset:512
	global_store_dwordx2 v[60:61], v[2:3], off offset:1024
	global_store_dwordx2 v[60:61], v[4:5], off offset:1536
	v_mul_f32_e32 v2, 0x45800000, v0
	v_cndmask_b32_e32 v0, v0, v2, vcc
	v_pk_mul_f32 v[2:3], v[38:39], v[0:1] op_sel_hi:[1,0]
	v_pk_mul_f32 v[4:5], v[40:41], v[0:1] op_sel_hi:[1,0]
	v_pk_mul_f32 v[2:3], v[188:189], v[2:3]
	v_pk_mul_f32 v[4:5], v[190:191], v[4:5]
	v_cvt_pk_bf16_f32 v2, v2, v3
	v_cvt_pk_bf16_f32 v3, v4, v5
	global_store_dwordx2 v[58:59], v[2:3], off
	v_pk_mul_f32 v[2:3], v[30:31], v[0:1] op_sel_hi:[1,0]
	v_pk_mul_f32 v[4:5], v[32:33], v[0:1] op_sel_hi:[1,0]
	v_pk_mul_f32 v[2:3], v[184:185], v[2:3]
	v_pk_mul_f32 v[4:5], v[186:187], v[4:5]
	v_cvt_pk_bf16_f32 v2, v2, v3
	v_cvt_pk_bf16_f32 v3, v4, v5
	global_store_dwordx2 v[58:59], v[2:3], off offset:512
	v_pk_mul_f32 v[2:3], v[26:27], v[0:1] op_sel_hi:[1,0]
	v_pk_mul_f32 v[4:5], v[28:29], v[0:1] op_sel_hi:[1,0]
	v_pk_mul_f32 v[2:3], v[180:181], v[2:3]
	v_pk_mul_f32 v[4:5], v[182:183], v[4:5]
	v_cvt_pk_bf16_f32 v2, v2, v3
	v_cvt_pk_bf16_f32 v3, v4, v5
	global_store_dwordx2 v[58:59], v[2:3], off offset:1024
	v_pk_mul_f32 v[2:3], v[10:11], v[0:1] op_sel_hi:[1,0]
	v_pk_mul_f32 v[4:5], v[12:13], v[0:1] op_sel_hi:[1,0]
	v_pk_mul_f32 v[2:3], v[176:177], v[2:3]
	v_pk_mul_f32 v[4:5], v[178:179], v[4:5]
	v_cvt_pk_bf16_f32 v2, v2, v3
	v_cvt_pk_bf16_f32 v3, v4, v5
	global_store_dwordx2 v[58:59], v[2:3], off offset:1536
	s_cmpk_lt_i32 s20, 0x400
	s_cbranch_scc0 .LBB0_148
	s_add_i32 s20, s20, s0
	s_cmpk_lt_i32 s20, 0x400
	s_cbranch_scc0 .Lrn_lastB
	v_lshlrev_b32_e32 v194, 12, v56
	v_lshl_add_u64 v[196:197], v[50:51], 0, v[194:195]
	global_load_dwordx4 v[14:17], v[196:197], off
	global_load_dwordx4 v[22:25], v[196:197], off offset:1024
	global_load_dwordx4 v[2:5], v[196:197], off offset:2048
	global_load_dwordx4 v[6:9], v[196:197], off offset:3072
	v_lshl_add_u64 v[198:199], v[196:197], 0, s[98:99]
	global_load_dwordx4 v[38:41], v[198:199], off
	global_load_dwordx4 v[30:33], v[198:199], off offset:1024
	global_load_dwordx4 v[26:29], v[198:199], off offset:2048
	global_load_dwordx4 v[10:13], v[198:199], off offset:3072
	v_lshlrev_b32_e32 v194, 11, v56
	v_lshl_add_u64 v[60:61], v[54:55], 0, v[194:195]
	v_lshl_add_u64 v[58:59], v[60:61], 0, s[100:101]
	v_add_u32_e32 v56, s1, v56
	s_waitcnt vmcnt(8)
	s_branch .Lrn_compB

; DI unsigned pack2(float a, float b) { fv2 v = {a, b}; return __builtin_bit_cast(unsigned, __builtin_convertvector(v, bfv2)); }
; DI float wave_sum_fast(float v) { v = fdpp_add(v, 0); v = fdpp_add(v, 1); v = fdpp_add(v, 2); v = fdpp_add(v, 3); v = xor16_sum(v); return xor32_sum(v); }
; DI void rmsnorm_rows(const float* x, const float* g, bf16_t* outb, float* outf) {
;     ...
;     for (int rr = 0; rr < 2; ++rr) {
; #pragma unroll
;       for (int i = 0; i < 4; ++i) ss[rr] += v[rr][i].x * v[rr][i].x + v[rr][i].y * v[rr][i].y + v[rr][i].z * v[rr][i].z + v[rr][i].w * v[rr][i].w;
;       ss[rr] = wave_sum_fast(ss[rr]);
;     }
; #pragma unroll
;     for (int rr = 0; rr < 2; ++rr) {
;       const int row = it * 16 + rr * 8 + w;
;       const float rs = rsqrtf(ss[rr] * (1.f / 1024.f) + 1e-6f);
; #pragma unroll
;       for (int i = 0; i < 4; ++i) {
;         const float o0 = v[rr][i].x * rs * gg[i].x, o1 = v[rr][i].y * rs * gg[i].y, o2 = v[rr][i].z * rs * gg[i].z, o3 = v[rr][i].w * rs * gg[i].w;
;         if (outf) { *(float4*)(outf + (size_t)row * 1024 + lane * 4 + 256 * i) = make_float4(o0, o1, o2, o3); }
;         else { uint2 o; o.x = pack2(o0, o1); o.y = pack2(o2, o3); *(uint2*)(outb + (size_t)row * 1024 + lane * 4 + 256 * i) = o; }
;       }
;     }
.Lrn_compB:
	v_pk_mul_f32 v[64:65], v[102:103], v[102:103]
	v_pk_mul_f32 v[68:69], v[110:111], v[110:111]
	v_pk_mul_f32 v[62:63], v[104:105], v[104:105]
	v_pk_mul_f32 v[72:73], v[94:95], v[94:95]
	v_pk_mul_f32 v[66:67], v[112:113], v[112:113]
	v_pk_mul_f32 v[70:71], v[90:91], v[90:91]
	v_pk_mul_f32 v[76:77], v[96:97], v[96:97]
	v_add_f32_e32 v0, v68, v69
	v_add_f32_e32 v57, v64, v65
	v_add_f32_e32 v87, v72, v73
	v_pk_mul_f32 v[64:65], v[126:127], v[126:127]
	v_pk_mul_f32 v[68:69], v[118:119], v[118:119]
	v_add_f32_e32 v86, v70, v71
	v_pk_mul_f32 v[70:71], v[114:115], v[114:115]
	v_pk_mul_f32 v[78:79], v[128:129], v[128:129]
	v_pk_mul_f32 v[80:81], v[120:121], v[120:121]
	v_add_f32_e32 v68, v68, v69
	v_add_f32_e32 v64, v64, v65
	v_add_f32_e32 v0, v0, v66
	v_add_f32_e32 v57, v57, v62
	v_add_f32_e32 v66, v87, v76
	v_pk_mul_f32 v[74:75], v[92:93], v[92:93]
	v_pk_mul_f32 v[72:73], v[98:99], v[98:99]
	v_pk_mul_f32 v[82:83], v[116:117], v[116:117]
	v_add_f32_e32 v65, v70, v71
	v_add_f32_e32 v0, v0, v67
	v_add_f32_e32 v57, v57, v63
	v_add_f32_e32 v63, v66, v77
	v_add_f32_e32 v66, v68, v80
	v_add_f32_e32 v64, v64, v78
	v_pk_mul_f32 v[84:85], v[100:101], v[100:101]
	v_add_f32_e32 v69, v72, v73
	v_add_f32_e32 v62, v86, v74
	v_add_f32_e32 v65, v65, v82
	v_add_f32_e32 v66, v66, v81
	v_add_f32_e32 v0, v57, v0
	v_add_f32_e32 v57, v64, v79
	v_add_f32_e32 v62, v62, v75
	v_add_f32_e32 v67, v69, v84
	v_add_f32_e32 v64, v65, v83
	v_add_f32_e32 v57, v57, v66
	v_add_f32_e32 v65, v67, v85
	v_add_f32_e32 v0, v0, v62
	v_add_f32_e32 v57, v57, v64
	v_add_f32_e32 v0, v0, v63
	v_add_f32_e32 v57, v57, v65
	s_nop 0
	v_add_f32_dpp v0, v0, v0 quad_perm:[1,0,3,2] row_mask:0xf bank_mask:0xf bound_ctrl:1
	v_add_f32_dpp v57, v57, v57 quad_perm:[1,0,3,2] row_mask:0xf bank_mask:0xf bound_ctrl:1
	s_nop 0
	v_add_f32_dpp v0, v0, v0 quad_perm:[2,3,0,1] row_mask:0xf bank_mask:0xf bound_ctrl:1
	v_add_f32_dpp v57, v57, v57 quad_perm:[2,3,0,1] row_mask:0xf bank_mask:0xf bound_ctrl:1
	s_nop 0
	v_add_f32_dpp v0, v0, v0 row_half_mirror row_mask:0xf bank_mask:0xf bound_ctrl:1
	v_add_f32_dpp v57, v57, v57 row_half_mirror row_mask:0xf bank_mask:0xf bound_ctrl:1
	s_nop 0
	v_add_f32_dpp v0, v0, v0 row_mirror row_mask:0xf bank_mask:0xf bound_ctrl:1
	v_add_f32_dpp v57, v57, v57 row_mirror row_mask:0xf bank_mask:0xf bound_ctrl:1
	v_mov_b32_e32 v62, v0
	v_mov_b32_e32 v64, v57
	s_nop 0
	v_permlane16_swap_b32_e32 v0, v62
	v_permlane16_swap_b32_e32 v57, v64
	v_add_f32_e32 v63, v0, v62
	v_add_f32_e32 v62, v57, v64
	v_mov_b32_e32 v65, v63
	v_mov_b32_e32 v64, v62
	s_nop 0
	v_permlane32_swap_b32_e32 v63, v65
	v_permlane32_swap_b32_e32 v62, v64
	v_pk_add_f32 v[62:63], v[62:63], v[64:65]
	s_nop 0
	v_pk_fma_f32 v[62:63], v[62:63], s[2:3], v[200:201] op_sel_hi:[1,0,0]
	s_nop 0
	v_mul_f32_e32 v0, 0x4b800000, v63
	v_cmp_gt_f32_e32 vcc, s3, v63
	s_nop 1
	v_cndmask_b32_e32 v0, v63, v0, vcc
	v_rsq_f32_e32 v0, v0
	s_nop 0
	v_mul_f32_e32 v57, 0x45800000, v0
	v_cndmask_b32_e32 v0, v0, v57, vcc
	v_pk_mul_f32 v[90:91], v[90:91], v[0:1] op_sel_hi:[1,0]
	v_pk_mul_f32 v[92:93], v[92:93], v[0:1] op_sel_hi:[1,0]
	v_pk_mul_f32 v[90:91], v[180:181], v[90:91]
	v_pk_mul_f32 v[92:93], v[182:183], v[92:93]
	v_pk_mul_f32 v[102:103], v[102:103], v[0:1] op_sel_hi:[1,0]
	v_pk_mul_f32 v[104:105], v[104:105], v[0:1] op_sel_hi:[1,0]
	v_pk_mul_f32 v[110:111], v[110:111], v[0:1] op_sel_hi:[1,0]
	v_pk_mul_f32 v[112:113], v[112:113], v[0:1] op_sel_hi:[1,0]
	v_cvt_pk_bf16_f32 v90, v90, v91
	v_cvt_pk_bf16_f32 v91, v92, v93
	v_pk_mul_f32 v[92:93], v[94:95], v[0:1] op_sel_hi:[1,0]
	v_pk_mul_f32 v[94:95], v[96:97], v[0:1] op_sel_hi:[1,0]
	v_mul_f32_e32 v0, 0x4b800000, v62
	v_cmp_gt_f32_e32 vcc, s3, v62
	v_pk_mul_f32 v[102:103], v[188:189], v[102:103]
	v_pk_mul_f32 v[104:105], v[190:191], v[104:105]
	v_cndmask_b32_e32 v0, v62, v0, vcc
	v_rsq_f32_e32 v0, v0
	v_pk_mul_f32 v[110:111], v[184:185], v[110:111]
	v_pk_mul_f32 v[112:113], v[186:187], v[112:113]
	v_cvt_pk_bf16_f32 v102, v102, v103
	v_cvt_pk_bf16_f32 v103, v104, v105
	v_cvt_pk_bf16_f32 v104, v110, v111
	v_cvt_pk_bf16_f32 v105, v112, v113
	v_pk_mul_f32 v[92:93], v[176:177], v[92:93]
	v_pk_mul_f32 v[94:95], v[178:179], v[94:95]
	v_cvt_pk_bf16_f32 v92, v92, v93
	v_cvt_pk_bf16_f32 v93, v94, v95
	global_store_dwordx2 v[148:149], v[102:103], off
	global_store_dwordx2 v[148:149], v[104:105], off offset:512
	global_store_dwordx2 v[148:149], v[90:91], off offset:1024
	global_store_dwordx2 v[148:149], v[92:93], off offset:1536
	v_mul_f32_e32 v90, 0x45800000, v0
	v_cndmask_b32_e32 v0, v0, v90, vcc
	v_pk_mul_f32 v[90:91], v[126:127], v[0:1] op_sel_hi:[1,0]
	v_pk_mul_f32 v[92:93], v[128:129], v[0:1] op_sel_hi:[1,0]
	v_pk_mul_f32 v[90:91], v[188:189], v[90:91]
	v_pk_mul_f32 v[92:93], v[190:191], v[92:93]
	v_cvt_pk_bf16_f32 v90, v90, v91
	v_cvt_pk_bf16_f32 v91, v92, v93
	global_store_dwordx2 v[146:147], v[90:91], off
	v_pk_mul_f32 v[90:91], v[118:119], v[0:1] op_sel_hi:[1,0]
	v_pk_mul_f32 v[92:93], v[120:121], v[0:1] op_sel_hi:[1,0]
	v_pk_mul_f32 v[90:91], v[184:185], v[90:91]
	v_pk_mul_f32 v[92:93], v[186:187], v[92:93]
	v_cvt_pk_bf16_f32 v90, v90, v91
	v_cvt_pk_bf16_f32 v91, v92, v93
	global_store_dwordx2 v[146:147], v[90:91], off offset:512
	v_pk_mul_f32 v[90:91], v[114:115], v[0:1] op_sel_hi:[1,0]
	v_pk_mul_f32 v[92:93], v[116:117], v[0:1] op_sel_hi:[1,0]
	v_pk_mul_f32 v[90:91], v[180:181], v[90:91]
	v_pk_mul_f32 v[92:93], v[182:183], v[92:93]
	v_cvt_pk_bf16_f32 v90, v90, v91
	v_cvt_pk_bf16_f32 v91, v92, v93
	global_store_dwordx2 v[146:147], v[90:91], off offset:1024
	v_pk_mul_f32 v[90:91], v[98:99], v[0:1] op_sel_hi:[1,0]
	v_pk_mul_f32 v[92:93], v[100:101], v[0:1] op_sel_hi:[1,0]
	v_pk_mul_f32 v[90:91], v[176:177], v[90:91]
	v_pk_mul_f32 v[92:93], v[178:179], v[92:93]
	v_cvt_pk_bf16_f32 v90, v90, v91
	v_cvt_pk_bf16_f32 v91, v92, v93
	global_store_dwordx2 v[146:147], v[90:91], off offset:1536
	s_cmpk_lt_i32 s20, 0x400
	s_cbranch_scc1 .Lrn_loop
